# FFN-up GEMM loop: all s_setprio removed (equal priority for MFMA and load waves), on v061
# speedup vs baseline: 1.0021x; 1.0021x over previous
.LBB0_587:
	s_add_u32 s90, s52, s4
	s_addc_u32 s91, s53, s5
	s_add_u32 s90, s90, 0x80080
	s_addc_u32 s91, s91, 0
	s_add_u32 s16, s52, s4
	s_addc_u32 s17, s53, s5
	s_add_u32 s16, s16, 0x100
	s_addc_u32 s17, s17, 0
	s_add_u32 s41, s21, s4
	s_addc_u32 s45, s74, s5
	s_add_i32 s51, 0, 0x10000
	s_cmpk_eq_i32 s4, 0xf00
	s_cselect_b32 s39, s61, s17
	s_cselect_b32 s38, s60, s16
	v_add_u32_e32 v156, s51, v157
	s_cselect_b32 s17, s31, s45
	s_cselect_b32 s16, s30, s41
	s_add_i32 s41, 0, 0x14000
	ds_read_b128 v[138:141], v156
	ds_read_b128 v[152:155], v156 offset:1024
	ds_read_b128 v[158:161], v156 offset:2048
	ds_read_b128 v[164:167], v156 offset:3072
	v_add_u32_e32 v156, s41, v157
	ds_read_b128 v[170:173], v156
	ds_read_b128 v[174:177], v156 offset:1024
	ds_read_b128 v[178:181], v156 offset:2048
	ds_read_b128 v[186:189], v156 offset:3072
	s_add_i32 m0, s58, 0xc000
	ds_read_b128 v[190:193], v184
	ds_read_b128 v[194:197], v184 offset:1024
	ds_read_b128 v[204:207], v184 offset:2048
	ds_read_b128 v[208:211], v184 offset:3072
	ds_read_b128 v[212:215], v184 offset:4096
	ds_read_b128 v[216:219], v184 offset:5120
	ds_read_b128 v[220:223], v184 offset:6144
	ds_read_b128 v[224:227], v184 offset:7168
	global_load_lds_dwordx4 v150, s[90:91]
	s_add_i32 m0, s58, 0xe000
	s_nop 0
	global_load_lds_dwordx4 v148, s[90:91]
	s_waitcnt vmcnt(8)
	s_waitcnt lgkmcnt(0)
	s_barrier
	v_mfma_f32_16x16x32_bf16 v[6:9], v[138:141], v[190:193], v[6:9]
	v_mfma_f32_16x16x32_bf16 v[130:133], v[158:161], v[190:193], v[130:133]
	v_mfma_f32_16x16x32_bf16 v[126:129], v[138:141], v[204:207], v[126:129]
	v_mfma_f32_16x16x32_bf16 v[122:125], v[158:161], v[204:207], v[122:125]
	v_mfma_f32_16x16x32_bf16 v[118:121], v[138:141], v[212:215], v[118:121]
	v_mfma_f32_16x16x32_bf16 v[114:117], v[158:161], v[212:215], v[114:117]
	v_mfma_f32_16x16x32_bf16 v[110:113], v[138:141], v[220:223], v[110:113]
	v_mfma_f32_16x16x32_bf16 v[106:109], v[158:161], v[220:223], v[106:109]
	v_mfma_f32_16x16x32_bf16 v[6:9], v[152:155], v[194:197], v[6:9]
	v_mfma_f32_16x16x32_bf16 v[130:133], v[164:167], v[194:197], v[130:133]
	v_mfma_f32_16x16x32_bf16 v[126:129], v[152:155], v[208:211], v[126:129]
	v_mfma_f32_16x16x32_bf16 v[122:125], v[164:167], v[208:211], v[122:125]
	v_mfma_f32_16x16x32_bf16 v[118:121], v[152:155], v[216:219], v[118:121]
	v_mfma_f32_16x16x32_bf16 v[114:117], v[164:167], v[216:219], v[114:117]
	v_mfma_f32_16x16x32_bf16 v[110:113], v[152:155], v[224:227], v[110:113]
	v_mfma_f32_16x16x32_bf16 v[106:109], v[164:167], v[224:227], v[106:109]
	v_mfma_f32_16x16x32_bf16 v[102:105], v[170:173], v[190:193], v[102:105]
	v_mfma_f32_16x16x32_bf16 v[98:101], v[178:181], v[190:193], v[98:101]
	v_mfma_f32_16x16x32_bf16 v[94:97], v[170:173], v[204:207], v[94:97]
	v_mfma_f32_16x16x32_bf16 v[90:93], v[178:181], v[204:207], v[90:93]
	v_mfma_f32_16x16x32_bf16 v[86:89], v[170:173], v[212:215], v[86:89]
	v_mfma_f32_16x16x32_bf16 v[82:85], v[178:181], v[212:215], v[82:85]
	v_mfma_f32_16x16x32_bf16 v[78:81], v[170:173], v[220:223], v[78:81]
	v_mfma_f32_16x16x32_bf16 v[74:77], v[178:181], v[220:223], v[74:77]
	v_mfma_f32_16x16x32_bf16 v[102:105], v[174:177], v[194:197], v[102:105]
	v_mfma_f32_16x16x32_bf16 v[98:101], v[186:189], v[194:197], v[98:101]
	v_mfma_f32_16x16x32_bf16 v[94:97], v[174:177], v[208:211], v[94:97]
	v_mfma_f32_16x16x32_bf16 v[90:93], v[186:189], v[208:211], v[90:93]
	v_mfma_f32_16x16x32_bf16 v[86:89], v[174:177], v[216:219], v[86:89]
	v_mfma_f32_16x16x32_bf16 v[82:85], v[186:189], v[216:219], v[82:85]
	v_mfma_f32_16x16x32_bf16 v[78:81], v[174:177], v[224:227], v[78:81]
	v_mfma_f32_16x16x32_bf16 v[74:77], v[186:189], v[224:227], v[74:77]
	s_barrier
	s_add_i32 s45, s51, s49
	s_mov_b32 m0, s45
	ds_read_b128 v[190:193], v184 offset:16384
	ds_read_b128 v[194:197], v184 offset:17408
	ds_read_b128 v[204:207], v184 offset:18432
	ds_read_b128 v[208:211], v184 offset:19456
	ds_read_b128 v[212:215], v184 offset:20480
	ds_read_b128 v[216:219], v184 offset:21504
	ds_read_b128 v[220:223], v184 offset:22528
	ds_read_b128 v[224:227], v184 offset:23552
	global_load_lds_dwordx4 v0, s[16:17]
	s_add_i32 m0, s45, 0x2000
	s_add_u32 s76, s16, 0x80000
	s_addc_u32 s77, s17, 0
	s_add_i32 s41, s41, s49
	global_load_lds_dwordx4 v144, s[16:17]
	s_mov_b32 m0, s41
	s_add_u32 s92, s38, s96
	s_addc_u32 s93, s39, s97
	global_load_lds_dwordx4 v0, s[76:77]
	s_add_i32 m0, s41, 0x2000
	s_nop 0
	global_load_lds_dwordx4 v144, s[76:77]
	s_mov_b32 m0, s58
	s_nop 0
	global_load_lds_dwordx4 v14, s[38:39]
	s_mov_b32 m0, s59
	s_nop 0
	global_load_lds_dwordx4 v142, s[38:39]
	s_waitcnt vmcnt(8)
	s_waitcnt lgkmcnt(0)
	s_barrier
	v_mfma_f32_16x16x32_bf16 v[70:73], v[138:141], v[190:193], v[70:73]
	v_mfma_f32_16x16x32_bf16 v[66:69], v[158:161], v[190:193], v[66:69]
	v_mfma_f32_16x16x32_bf16 v[62:65], v[138:141], v[204:207], v[62:65]
	v_mfma_f32_16x16x32_bf16 v[58:61], v[158:161], v[204:207], v[58:61]
	v_mfma_f32_16x16x32_bf16 v[54:57], v[138:141], v[212:215], v[54:57]
	v_mfma_f32_16x16x32_bf16 v[50:53], v[158:161], v[212:215], v[50:53]
	v_mfma_f32_16x16x32_bf16 v[46:49], v[138:141], v[220:223], v[46:49]
	v_mfma_f32_16x16x32_bf16 v[42:45], v[158:161], v[220:223], v[42:45]
	v_mfma_f32_16x16x32_bf16 v[70:73], v[152:155], v[194:197], v[70:73]
	v_mfma_f32_16x16x32_bf16 v[66:69], v[164:167], v[194:197], v[66:69]
	v_mfma_f32_16x16x32_bf16 v[62:65], v[152:155], v[208:211], v[62:65]
	v_mfma_f32_16x16x32_bf16 v[58:61], v[164:167], v[208:211], v[58:61]
	v_mfma_f32_16x16x32_bf16 v[54:57], v[152:155], v[216:219], v[54:57]
	v_mfma_f32_16x16x32_bf16 v[50:53], v[164:167], v[216:219], v[50:53]
	v_mfma_f32_16x16x32_bf16 v[46:49], v[152:155], v[224:227], v[46:49]
	v_mfma_f32_16x16x32_bf16 v[42:45], v[164:167], v[224:227], v[42:45]
	v_mfma_f32_16x16x32_bf16 v[38:41], v[170:173], v[190:193], v[38:41]
	v_mfma_f32_16x16x32_bf16 v[34:37], v[178:181], v[190:193], v[34:37]
	v_mfma_f32_16x16x32_bf16 v[30:33], v[170:173], v[204:207], v[30:33]
	v_mfma_f32_16x16x32_bf16 v[26:29], v[178:181], v[204:207], v[26:29]
	v_mfma_f32_16x16x32_bf16 v[22:25], v[170:173], v[212:215], v[22:25]
	v_mfma_f32_16x16x32_bf16 v[18:21], v[178:181], v[212:215], v[18:21]
	v_mfma_f32_16x16x32_bf16 v[10:13], v[170:173], v[220:223], v[10:13]
	v_mfma_f32_16x16x32_bf16 v[2:5], v[178:181], v[220:223], v[2:5]
	v_mfma_f32_16x16x32_bf16 v[38:41], v[174:177], v[194:197], v[38:41]
	v_mfma_f32_16x16x32_bf16 v[34:37], v[186:189], v[194:197], v[34:37]
	v_mfma_f32_16x16x32_bf16 v[30:33], v[174:177], v[208:211], v[30:33]
	v_mfma_f32_16x16x32_bf16 v[26:29], v[186:189], v[208:211], v[26:29]
	v_mfma_f32_16x16x32_bf16 v[22:25], v[174:177], v[216:219], v[22:25]
	v_mfma_f32_16x16x32_bf16 v[18:21], v[186:189], v[216:219], v[18:21]
	v_mfma_f32_16x16x32_bf16 v[10:13], v[174:177], v[224:227], v[10:13]
	v_mfma_f32_16x16x32_bf16 v[2:5], v[186:189], v[224:227], v[2:5]
	s_barrier
	s_add_i32 s41, 0, 0x18000
	v_add_u32_e32 v156, s41, v157
	s_add_i32 s45, 0, 0x1c000
	ds_read_b128 v[138:141], v156
	ds_read_b128 v[152:155], v156 offset:1024
	ds_read_b128 v[158:161], v156 offset:2048
	ds_read_b128 v[164:167], v156 offset:3072
	v_add_u32_e32 v156, s45, v157
	ds_read_b128 v[170:173], v156
	ds_read_b128 v[174:177], v156 offset:1024
	ds_read_b128 v[178:181], v156 offset:2048
	ds_read_b128 v[186:189], v156 offset:3072
	s_add_u32 s38, s38, 0x80000
	s_addc_u32 s39, s39, 0
	s_mov_b32 m0, s62
	ds_read_b128 v[190:193], v184 offset:32768
	ds_read_b128 v[194:197], v184 offset:33792
	ds_read_b128 v[204:207], v184 offset:34816
	ds_read_b128 v[208:211], v184 offset:35840
	ds_read_b128 v[212:215], v184 offset:36864
	ds_read_b128 v[216:219], v184 offset:37888
	ds_read_b128 v[220:223], v184 offset:38912
	ds_read_b128 v[224:227], v184 offset:39936
	global_load_lds_dwordx4 v14, s[38:39]
	s_mov_b32 m0, s63
	s_nop 0
	global_load_lds_dwordx4 v142, s[38:39]
	s_waitcnt vmcnt(8)
	s_waitcnt lgkmcnt(0)
	s_barrier
	v_mfma_f32_16x16x32_bf16 v[6:9], v[138:141], v[190:193], v[6:9]
	v_mfma_f32_16x16x32_bf16 v[130:133], v[158:161], v[190:193], v[130:133]
	v_mfma_f32_16x16x32_bf16 v[126:129], v[138:141], v[204:207], v[126:129]
	v_mfma_f32_16x16x32_bf16 v[122:125], v[158:161], v[204:207], v[122:125]
	v_mfma_f32_16x16x32_bf16 v[118:121], v[138:141], v[212:215], v[118:121]
	v_mfma_f32_16x16x32_bf16 v[114:117], v[158:161], v[212:215], v[114:117]
	v_mfma_f32_16x16x32_bf16 v[110:113], v[138:141], v[220:223], v[110:113]
	v_mfma_f32_16x16x32_bf16 v[106:109], v[158:161], v[220:223], v[106:109]
	v_mfma_f32_16x16x32_bf16 v[6:9], v[152:155], v[194:197], v[6:9]
	v_mfma_f32_16x16x32_bf16 v[130:133], v[164:167], v[194:197], v[130:133]
	v_mfma_f32_16x16x32_bf16 v[126:129], v[152:155], v[208:211], v[126:129]
	v_mfma_f32_16x16x32_bf16 v[122:125], v[164:167], v[208:211], v[122:125]
	v_mfma_f32_16x16x32_bf16 v[118:121], v[152:155], v[216:219], v[118:121]
	v_mfma_f32_16x16x32_bf16 v[114:117], v[164:167], v[216:219], v[114:117]
	v_mfma_f32_16x16x32_bf16 v[110:113], v[152:155], v[224:227], v[110:113]
	v_mfma_f32_16x16x32_bf16 v[106:109], v[164:167], v[224:227], v[106:109]
	v_mfma_f32_16x16x32_bf16 v[102:105], v[170:173], v[190:193], v[102:105]
	v_mfma_f32_16x16x32_bf16 v[98:101], v[178:181], v[190:193], v[98:101]
	v_mfma_f32_16x16x32_bf16 v[94:97], v[170:173], v[204:207], v[94:97]
	v_mfma_f32_16x16x32_bf16 v[90:93], v[178:181], v[204:207], v[90:93]
	v_mfma_f32_16x16x32_bf16 v[86:89], v[170:173], v[212:215], v[86:89]
	v_mfma_f32_16x16x32_bf16 v[82:85], v[178:181], v[212:215], v[82:85]
	v_mfma_f32_16x16x32_bf16 v[78:81], v[170:173], v[220:223], v[78:81]
	v_mfma_f32_16x16x32_bf16 v[74:77], v[178:181], v[220:223], v[74:77]
	v_mfma_f32_16x16x32_bf16 v[102:105], v[174:177], v[194:197], v[102:105]
	v_mfma_f32_16x16x32_bf16 v[98:101], v[186:189], v[194:197], v[98:101]
	v_mfma_f32_16x16x32_bf16 v[94:97], v[174:177], v[208:211], v[94:97]
	v_mfma_f32_16x16x32_bf16 v[90:93], v[186:189], v[208:211], v[90:93]
	v_mfma_f32_16x16x32_bf16 v[86:89], v[174:177], v[216:219], v[86:89]
	v_mfma_f32_16x16x32_bf16 v[82:85], v[186:189], v[216:219], v[82:85]
	v_mfma_f32_16x16x32_bf16 v[78:81], v[174:177], v[224:227], v[78:81]
	v_mfma_f32_16x16x32_bf16 v[74:77], v[186:189], v[224:227], v[74:77]
	s_barrier
	s_add_i32 s38, s41, s49
	s_add_u32 s90, s16, s96
	s_addc_u32 s91, s17, s97
	s_mov_b32 m0, s38
	ds_read_b128 v[190:193], v184 offset:49152
	ds_read_b128 v[194:197], v184 offset:50176
	ds_read_b128 v[204:207], v184 offset:51200
	ds_read_b128 v[208:211], v184 offset:52224
	ds_read_b128 v[212:215], v184 offset:53248
	ds_read_b128 v[216:219], v184 offset:54272
	ds_read_b128 v[220:223], v184 offset:55296
	ds_read_b128 v[224:227], v184 offset:56320
	global_load_lds_dwordx4 v0, s[90:91]
	s_add_i32 m0, s38, 0x2000
	s_add_u32 s16, s16, 0x80080
	s_addc_u32 s17, s17, 0
	s_add_i32 s38, s45, s49
	global_load_lds_dwordx4 v144, s[90:91]
	s_mov_b32 m0, s38
	s_nop 0
	global_load_lds_dwordx4 v0, s[16:17]
	s_add_i32 m0, s38, 0x2000
	s_nop 0
	global_load_lds_dwordx4 v144, s[16:17]
	s_mov_b32 m0, s68
	s_nop 0
	global_load_lds_dwordx4 v14, s[92:93]
	s_mov_b32 m0, s69
	s_nop 0
	global_load_lds_dwordx4 v142, s[92:93]
	s_waitcnt vmcnt(8)
	s_waitcnt lgkmcnt(0)
	s_barrier
	v_mfma_f32_16x16x32_bf16 v[70:73], v[138:141], v[190:193], v[70:73]
	v_mfma_f32_16x16x32_bf16 v[66:69], v[158:161], v[190:193], v[66:69]
	v_mfma_f32_16x16x32_bf16 v[62:65], v[138:141], v[204:207], v[62:65]
	v_mfma_f32_16x16x32_bf16 v[58:61], v[158:161], v[204:207], v[58:61]
	v_mfma_f32_16x16x32_bf16 v[54:57], v[138:141], v[212:215], v[54:57]
	v_mfma_f32_16x16x32_bf16 v[50:53], v[158:161], v[212:215], v[50:53]
	v_mfma_f32_16x16x32_bf16 v[46:49], v[138:141], v[220:223], v[46:49]
	v_mfma_f32_16x16x32_bf16 v[42:45], v[158:161], v[220:223], v[42:45]
	v_mfma_f32_16x16x32_bf16 v[70:73], v[152:155], v[194:197], v[70:73]
	v_mfma_f32_16x16x32_bf16 v[66:69], v[164:167], v[194:197], v[66:69]
	v_mfma_f32_16x16x32_bf16 v[62:65], v[152:155], v[208:211], v[62:65]
	v_mfma_f32_16x16x32_bf16 v[58:61], v[164:167], v[208:211], v[58:61]
	v_mfma_f32_16x16x32_bf16 v[54:57], v[152:155], v[216:219], v[54:57]
	v_mfma_f32_16x16x32_bf16 v[50:53], v[164:167], v[216:219], v[50:53]
	v_mfma_f32_16x16x32_bf16 v[46:49], v[152:155], v[224:227], v[46:49]
	v_mfma_f32_16x16x32_bf16 v[42:45], v[164:167], v[224:227], v[42:45]
	v_mfma_f32_16x16x32_bf16 v[38:41], v[170:173], v[190:193], v[38:41]
	v_mfma_f32_16x16x32_bf16 v[34:37], v[178:181], v[190:193], v[34:37]
	v_mfma_f32_16x16x32_bf16 v[30:33], v[170:173], v[204:207], v[30:33]
	v_mfma_f32_16x16x32_bf16 v[26:29], v[178:181], v[204:207], v[26:29]
	v_mfma_f32_16x16x32_bf16 v[22:25], v[170:173], v[212:215], v[22:25]
	v_mfma_f32_16x16x32_bf16 v[18:21], v[178:181], v[212:215], v[18:21]
	v_mfma_f32_16x16x32_bf16 v[10:13], v[170:173], v[220:223], v[10:13]
	v_mfma_f32_16x16x32_bf16 v[2:5], v[178:181], v[220:223], v[2:5]
	v_mfma_f32_16x16x32_bf16 v[38:41], v[174:177], v[194:197], v[38:41]
	v_mfma_f32_16x16x32_bf16 v[34:37], v[186:189], v[194:197], v[34:37]
	v_mfma_f32_16x16x32_bf16 v[30:33], v[174:177], v[208:211], v[30:33]
	v_mfma_f32_16x16x32_bf16 v[26:29], v[186:189], v[208:211], v[26:29]
	v_mfma_f32_16x16x32_bf16 v[22:25], v[174:177], v[216:219], v[22:25]
	v_mfma_f32_16x16x32_bf16 v[18:21], v[186:189], v[216:219], v[18:21]
	v_mfma_f32_16x16x32_bf16 v[10:13], v[174:177], v[224:227], v[10:13]
	v_mfma_f32_16x16x32_bf16 v[2:5], v[186:189], v[224:227], v[2:5]
	s_barrier
	s_add_i32 s40, s40, 2
	s_add_u32 s4, s4, 0x100
	s_addc_u32 s5, s5, 0
	s_cmp_gt_u32 s40, 29
	s_cbranch_scc0 .LBB0_587
	s_and_b64 vcc, exec, s[26:27]
	s_cbranch_vccz .LBB0_590
	s_barrier
